# P2 rows loop: loop-invariant g_q_a/g_kv_a loads hoisted, first-row rotary unpack deferred, rope-table loads issued early
# speedup vs baseline: 1.0498x; 1.0035x over previous
; __device__ __forceinline__ unsigned pk2(float lo, float hi) { f32x2_t v = {lo, hi}; bf16x2_t b = __builtin_convertvector(v, bf16x2_t); return __builtin_bit_cast(unsigned, b); }
; __device__ __forceinline__ float bflo(unsigned w) { return __uint_as_float(w << 16); }
; __device__ __forceinline__ float bfhi(unsigned w) { return __uint_as_float(w & 0xffff0000u); }
; #define A (*args_opaque((CArgs*)__builtin_amdgcn_kernarg_segment_ptr()))
; __device__ __forceinline__ void p2_rows(ArgsRef A, int lane, int wave) {
;     unsigned char* ws = A.ws; const int gw = blockIdx.x * 8 + wave, NGW = gridDim.x * 8;
;     const bf16_t* H1 = (const bf16_t*)(ws + WS_H1); bf16_t* CQ = (bf16_t*)(ws + WS_CQ); bf16_t* CKV = (bf16_t*)(ws + WS_CKV);
;     float* KROT = (float*)(ws + WS_KROT); float* ROTSS = (float*)(ws + WS_ROTSS); const float* RP = (const float*)(ws + WS_ROPE);
;     for (int r0 = gw; r0 < MV; r0 += 2 * NGW) {
;       u32x4 qw[2], kw[2]; unsigned pe1[2], pe2[2];
; #pragma unroll
;       for (int u = 0; u < 2; ++u) { const int r = r0 + u * NGW; qw[u] = (u32x4){0, 0, 0, 0}; kw[u] = (u32x4){0, 0, 0, 0}; pe1[u] = 0; pe2[u] = 0;
;         if (r < MV) { const bf16_t* hrow = H1 + (size_t)r * NIN; if (lane < 48) qw[u] = *(const u32x4*)(hrow + lane * 8); if (lane < 32) kw[u] = *(const u32x4*)(hrow + 384 + lane * 8); if (lane < 16) { pe1[u] = hrow[1152 + lane]; pe2[u] = hrow[1168 + lane]; } } }
;     ...
;           if (lane < 48) { const f32x4 g0 = *(const f32x4*)(A.in[9] + lane * 8), g1 = *(const f32x4*)(A.in[9] + lane * 8 + 4);
;             u32x4 o; o.x = pk2(v[0] * rs * g0.x, v[1] * rs * g0.y); o.y = pk2(v[2] * rs * g0.z, v[3] * rs * g0.w); o.z = pk2(v[4] * rs * g1.x, v[5] * rs * g1.y); o.w = pk2(v[6] * rs * g1.z, v[7] * rs * g1.w);
;             *(u32x4*)(CQ + (size_t)r * 384 + lane * 8) = o; } }
;         { const u32x4 w = kw[u]; float v[8]; v[0] = bflo(w.x); v[1] = bfhi(w.x); v[2] = bflo(w.y); v[3] = bfhi(w.y); v[4] = bflo(w.z); v[5] = bfhi(w.z); v[6] = bflo(w.w); v[7] = bfhi(w.w); float ss = 0.f;
; #pragma unroll
;           for (int k = 0; k < 8; ++k) ss += v[k] * v[k];
;           const float rs = rsqrtf(wave_sum(ss) * (1.f / 256.f) + EPSF);
;           if (lane < 32) { const f32x4 g0 = *(const f32x4*)(A.in[11] + lane * 8), g1 = *(const f32x4*)(A.in[11] + lane * 8 + 4);
.LBB0_280:
	s_or_b64 exec, exec, s[30:31]
	s_waitcnt lgkmcnt(0)
	s_barrier
	v_mbcnt_lo_u32_b32 v0, -1, 0
	v_mbcnt_hi_u32_b32 v0, -1, v0
	s_mov_b64 s[30:31], s[92:93]
	v_add_u32_e32 v0, s94, v0
	s_andn2_b64 vcc, exec, s[28:29]
	s_cbranch_vccnz .LBB0_325
	s_load_dwordx4 s[52:55], s[30:31], 0xf8
	s_load_dwordx2 s[24:25], s[30:31], 0x48
	v_and_b32_e32 v16, 63, v0
	s_load_dwordx2 s[30:31], s[30:31], 0x58
	v_mov_b32_e32 v19, 0
	v_lshlrev_b32_e32 v18, 5, v16
	v_lshlrev_b32_e32 v0, 4, v16
	v_mov_b32_e32 v1, v19
	s_waitcnt lgkmcnt(0)
	v_lshl_add_u64 v[22:23], s[24:25], 0, v[18:19]
	v_lshl_add_u64 v[2:3], s[54:55], 0, v[0:1]
	s_mov_b64 s[24:25], 0x8000000
	v_lshl_add_u64 v[26:27], s[30:31], 0, v[18:19]
	s_mov_b64 s[30:31], 0x8c80000
	v_lshlrev_b32_e32 v18, 2, v16
	v_lshl_add_u64 v[24:25], v[2:3], 0, s[24:25]
	v_lshl_add_u64 v[28:29], v[2:3], 0, s[30:31]
	v_lshl_add_u64 v[2:3], s[54:55], 0, v[18:19]
	s_mov_b64 s[30:31], 0x3100000
	v_lshl_add_u64 v[30:31], v[2:3], 0, s[30:31]
	v_mbcnt_hi_u32_b32 v2, -1, v212
	v_and_b32_e32 v3, 64, v2
	v_add_u32_e32 v3, 64, v3
	v_xor_b32_e32 v4, 1, v2
	v_cmp_lt_i32_e32 vcc, v4, v3
	s_add_u32 s1, s54, 0x3600000
	s_addc_u32 s4, s55, 0
	v_cndmask_b32_e32 v4, v2, v4, vcc
	v_lshlrev_b32_e32 v17, 2, v4
	v_xor_b32_e32 v4, 2, v2
	v_cmp_lt_i32_e32 vcc, v4, v3
	s_add_u32 s5, s54, 0x3510000
	v_mov_b32_e32 v50, 0x300
	v_cndmask_b32_e32 v4, v2, v4, vcc
	v_lshlrev_b32_e32 v21, 2, v4
	v_xor_b32_e32 v4, 4, v2
	v_cmp_lt_i32_e32 vcc, v4, v3
	s_addc_u32 s23, s55, 0
	s_add_u32 s28, s54, 0x1800000
	v_cndmask_b32_e32 v4, v2, v4, vcc
	v_lshlrev_b32_e32 v46, 2, v4
	v_xor_b32_e32 v4, 8, v2
	v_cmp_lt_i32_e32 vcc, v4, v3
	s_addc_u32 s29, s55, 0
	s_ashr_i32 s79, s78, 31
	v_cndmask_b32_e32 v4, v2, v4, vcc
	v_lshlrev_b32_e32 v47, 2, v4
	v_xor_b32_e32 v4, 16, v2
	v_cmp_lt_i32_e32 vcc, v4, v3
	s_mul_i32 s31, s78, 0xa00
	v_cmp_gt_u32_e64 s[38:39], 48, v16
	v_cndmask_b32_e32 v4, v2, v4, vcc
	v_lshlrev_b32_e32 v48, 2, v4
	v_xor_b32_e32 v4, 32, v2
	v_cmp_lt_i32_e32 vcc, v4, v3
	v_lshlrev_b32_e32 v20, 3, v16
	v_cmp_gt_u32_e64 s[40:41], 32, v16
	v_cndmask_b32_e32 v2, v2, v4, vcc
	v_lshlrev_b32_e32 v49, 2, v2
	v_mad_i64_i32 v[2:3], s[34:35], s78, v50, v[0:1]
	v_lshl_add_u64 v[32:33], v[2:3], 0, s[24:25]
	v_mov_b32_e32 v2, 0xa00
	s_mul_hi_i32 s25, s78, 0xa00
	v_mad_i64_i32 v[34:35], s[36:37], s78, v2, v[0:1]
	v_cmp_gt_u32_e64 s[42:43], 16, v16
	v_cmp_eq_u32_e64 s[44:45], 0, v16
	s_add_i32 s30, s78, 0xffffc000
	s_ashr_i32 s24, s0, 31
	s_mul_hi_i32 s35, s0, 0x300
	s_mul_i32 s34, s0, 0x300
	s_mul_hi_i32 s37, s0, 0xa00
	s_mul_i32 s36, s0, 0xa00
	v_lshl_or_b32 v36, v16, 1, s31
	v_mov_b32_e32 v37, s25
	s_mov_b32 s47, 0
	v_mov_b32_e32 v51, 0x358637bd
	s_mov_b32 s25, 0x800000
	s_mov_b64 s[48:49], s[78:79]
	s_mov_b64 s[72:73], exec
	s_and_b64 exec, s[72:73], s[38:39]
	global_load_dwordx4 v[130:133], v[22:23], off
	global_load_dwordx4 v[134:137], v[22:23], off offset:16
	s_and_b64 exec, s[72:73], s[40:41]
	global_load_dwordx4 v[138:141], v[26:27], off
	global_load_dwordx4 v[142:145], v[26:27], off offset:16
	s_mov_b64 exec, s[72:73]
	s_branch .LBB0_284

; __device__ __forceinline__ void p2_rows(ArgsRef A, int lane, int wave) {
;     ...
;         if (r < MV) { const bf16_t* hrow = H1 + (size_t)r * NIN; if (lane < 48) qw[u] = *(const u32x4*)(hrow + lane * 8); if (lane < 32) kw[u] = *(const u32x4*)(hrow + 384 + lane * 8); if (lane < 16) { pe1[u] = hrow[1152 + lane]; pe2[u] = hrow[1168 + lane]; } } }
.LBB0_288:
	s_or_b64 exec, exec, s[56:57]
	v_mov_b32_e32 v41, 0
	s_and_saveexec_b64 s[56:57], s[42:43]
	s_cbranch_execz .LBB0_290
	v_lshl_add_u64 v[0:1], s[54:55], 0, v[36:37]
	v_add_co_u32_e32 v0, vcc, 0x3600000, v0
	s_nop 1
	v_addc_co_u32_e32 v1, vcc, 0, v1, vcc
	global_load_ushort v146, v[0:1], off offset:2304
	s_nop 0
	global_load_ushort v147, v[0:1], off offset:2336

; #define A (*args_opaque((CArgs*)__builtin_amdgcn_kernarg_segment_ptr()))
; __device__ __forceinline__ void p2_rows(ArgsRef A, int lane, int wave) {
;     ...
;       for (int u = 0; u < 2; ++u) { const int r = r0 + u * NGW; if (r < MV) {
;         int pos; size_t kvrow; float* okv; float* okr;
;         if (r < MPR) { pos = r & 4095; kvrow = (size_t)r; okv = A.out + O_KVP + (size_t)r * 256; okr = A.out + O_KRP + (size_t)r * 32; }
;         else { const int s = r - MPR, b = s >> 4, t = s & 15; pos = 2048 + t; kvrow = (size_t)(16384 + b * SKVB + 2048 + t); okv = A.out + O_KVS + (size_t)s * 256; okr = A.out + O_KRS + (size_t)s * 32; }
;         { const u32x4 w = qw[u]; float v[8]; v[0] = bflo(w.x); v[1] = bfhi(w.x); v[2] = bflo(w.y); v[3] = bfhi(w.y); v[4] = bflo(w.z); v[5] = bfhi(w.z); v[6] = bflo(w.w); v[7] = bfhi(w.w); float ss = 0.f;
; #pragma unroll
;           for (int k = 0; k < 8; ++k) ss += v[k] * v[k];
;           const float rs = rsqrtf(wave_sum(ss) * (1.f / 384.f) + EPSF);
;           if (lane < 48) { const f32x4 g0 = *(const f32x4*)(A.in[9] + lane * 8), g1 = *(const f32x4*)(A.in[9] + lane * 8 + 4);
;             u32x4 o; o.x = pk2(v[0] * rs * g0.x, v[1] * rs * g0.y); o.y = pk2(v[2] * rs * g0.z, v[3] * rs * g0.w); o.z = pk2(v[4] * rs * g1.x, v[5] * rs * g1.y); o.w = pk2(v[6] * rs * g1.z, v[7] * rs * g1.w);
;             *(u32x4*)(CQ + (size_t)r * 384 + lane * 8) = o; } }
;         { const u32x4 w = kw[u]; float v[8]; v[0] = bflo(w.x); v[1] = bfhi(w.x); v[2] = bflo(w.y); v[3] = bfhi(w.y); v[4] = bflo(w.z); v[5] = bfhi(w.z); v[6] = bflo(w.w); v[7] = bfhi(w.w); float ss = 0.f;
; #pragma unroll
;           for (int k = 0; k < 8; ++k) ss += v[k] * v[k];
;           const float rs = rsqrtf(wave_sum(ss) * (1.f / 256.f) + EPSF);
;           if (lane < 32) { const f32x4 g0 = *(const f32x4*)(A.in[11] + lane * 8), g1 = *(const f32x4*)(A.in[11] + lane * 8 + 4);
;             f32x4 c0, c1; c0.x = v[0] * rs * g0.x; c0.y = v[1] * rs * g0.y; c0.z = v[2] * rs * g0.z; c0.w = v[3] * rs * g0.w; c1.x = v[4] * rs * g1.x; c1.y = v[5] * rs * g1.y; c1.z = v[6] * rs * g1.z; c1.w = v[7] * rs * g1.w;
;             *(f32x4*)(okv + lane * 8) = c0; *(f32x4*)(okv + lane * 8 + 4) = c1;
;             u32x4 o; o.x = pk2(c0.x, c0.y); o.y = pk2(c0.z, c0.w); o.z = pk2(c1.x, c1.y); o.w = pk2(c1.z, c1.w);
;             *(u32x4*)(CKV + kvrow * 256 + lane * 8) = o; } }
;         { float ss = 0.f;
.LBB0_303:
	s_mov_b64 s[72:73], exec
	s_and_b64 exec, s[72:73], s[42:43]
	v_lshl_or_b32 v152, s33, 5, v16
	v_mov_b32_e32 v153, 0
	v_lshl_add_u64 v[152:153], v[152:153], 2, s[28:29]
	global_load_dword v148, v[152:153], off offset:64
	global_load_dword v150, v[152:153], off
	s_waitcnt vmcnt(0)
	v_lshlrev_b32_e32 v40, 16, v146
	v_lshlrev_b32_e32 v41, 16, v147
	s_mov_b64 exec, s[72:73]
	v_lshlrev_b32_e32 v42, 16, v12
	v_and_b32_e32 v43, 0xffff0000, v12
	v_lshlrev_b32_e32 v44, 16, v13
	v_and_b32_e32 v45, 0xffff0000, v13
	v_pk_mul_f32 v[52:53], v[42:43], v[42:43]
	v_pk_mul_f32 v[54:55], v[44:45], v[44:45]
	v_add_f32_e32 v18, v52, v53
	v_lshlrev_b32_e32 v12, 16, v14
	v_and_b32_e32 v13, 0xffff0000, v14
	v_add_f32_e32 v18, v54, v18
	v_pk_mul_f32 v[56:57], v[12:13], v[12:13]
	v_add_f32_e32 v18, v55, v18
	v_lshlrev_b32_e32 v14, 16, v15
	v_and_b32_e32 v15, 0xffff0000, v15
	v_add_f32_e32 v18, v56, v18
	v_pk_mul_f32 v[58:59], v[14:15], v[14:15]
	v_add_f32_e32 v18, v57, v18
	v_add_f32_e32 v18, v58, v18
	v_add_f32_e32 v18, v59, v18
	s_nop 1
	v_add_f32_dpp v52, v18, v18 quad_perm:[1,0,3,2] row_mask:0xf bank_mask:0xf
	s_nop 1
	v_add_f32_dpp v52, v52, v52 quad_perm:[2,3,0,1] row_mask:0xf bank_mask:0xf
	s_nop 1
	v_add_f32_dpp v52, v52, v52 row_half_mirror row_mask:0xf bank_mask:0xf
	s_nop 1
	v_add_f32_dpp v52, v52, v52 row_mirror row_mask:0xf bank_mask:0xf
	s_nop 1
	v_add_f32_dpp v52, v52, v52 row_bcast:15 row_mask:0xa bank_mask:0xf
	s_nop 1
	v_add_f32_dpp v52, v52, v52 row_bcast:31 row_mask:0xc bank_mask:0xf
	s_nop 1
	v_readlane_b32 vcc_lo, v52, 63
	s_nop 1
	v_mov_b32_e32 v18, vcc_lo
	v_mov_b32_e32 v52, 0
	s_and_saveexec_b64 s[76:77], s[38:39]
	s_cbranch_execz .LBB0_305
	s_waitcnt lgkmcnt(0)
	v_add_f32_e32 v18, v18, v52
	v_fmamk_f32 v18, v18, 0x3b2aaaab, v51
	v_mul_f32_e32 v52, 0x4b800000, v18
	v_cmp_gt_f32_e32 vcc, s25, v18
	s_nop 1
	v_cndmask_b32_e32 v18, v18, v52, vcc
	v_rsq_f32_e32 v18, v18
	s_nop 0
	v_mul_f32_e32 v52, 0x45800000, v18
	v_cndmask_b32_e32 v18, v18, v52, vcc
	v_pk_mul_f32 v[42:43], v[18:19], v[42:43] op_sel_hi:[0,1]
	v_pk_mul_f32 v[44:45], v[18:19], v[44:45] op_sel_hi:[0,1]
	v_pk_mul_f32 v[12:13], v[18:19], v[12:13] op_sel_hi:[0,1]
	v_pk_mul_f32 v[14:15], v[18:19], v[14:15] op_sel_hi:[0,1]
	v_pk_mul_f32 v[42:43], v[42:43], v[130:131]
	v_pk_mul_f32 v[44:45], v[44:45], v[132:133]
	v_pk_mul_f32 v[52:53], v[12:13], v[134:135]
	v_pk_mul_f32 v[54:55], v[14:15], v[136:137]
	v_cvt_pk_bf16_f32 v12, v42, v43
	v_cvt_pk_bf16_f32 v13, v44, v45
	v_cvt_pk_bf16_f32 v14, v52, v53
	v_cvt_pk_bf16_f32 v15, v54, v55
	v_lshl_add_u64 v[42:43], s[54:55], 0, v[32:33]
	global_store_dwordx4 v[42:43], v[12:15], off
.LBB0_305:
	s_or_b64 exec, exec, s[76:77]
	s_nop 0
	v_lshlrev_b32_e32 v12, 16, v8
	v_and_b32_e32 v13, 0xffff0000, v8
	v_lshlrev_b32_e32 v8, 16, v9
	v_and_b32_e32 v9, 0xffff0000, v9
	v_pk_mul_f32 v[42:43], v[12:13], v[12:13]
	v_pk_mul_f32 v[44:45], v[8:9], v[8:9]
	v_add_f32_e32 v18, v42, v43
	v_lshlrev_b32_e32 v14, 16, v10
	v_and_b32_e32 v15, 0xffff0000, v10
	v_add_f32_e32 v18, v44, v18
	s_waitcnt lgkmcnt(0)
	v_pk_mul_f32 v[52:53], v[14:15], v[14:15]
	v_add_f32_e32 v18, v45, v18
	v_lshlrev_b32_e32 v10, 16, v11
	v_and_b32_e32 v11, 0xffff0000, v11
	v_add_f32_e32 v18, v52, v18
	v_pk_mul_f32 v[54:55], v[10:11], v[10:11]
	v_add_f32_e32 v18, v53, v18
	v_add_f32_e32 v18, v54, v18
	v_add_f32_e32 v18, v55, v18
	s_nop 1
	v_add_f32_dpp v42, v18, v18 quad_perm:[1,0,3,2] row_mask:0xf bank_mask:0xf
	s_nop 1
	v_add_f32_dpp v42, v42, v42 quad_perm:[2,3,0,1] row_mask:0xf bank_mask:0xf
	s_nop 1
	v_add_f32_dpp v42, v42, v42 row_half_mirror row_mask:0xf bank_mask:0xf
	s_nop 1
	v_add_f32_dpp v42, v42, v42 row_mirror row_mask:0xf bank_mask:0xf
	s_nop 1
	v_add_f32_dpp v42, v42, v42 row_bcast:15 row_mask:0xa bank_mask:0xf
	s_nop 1
	v_add_f32_dpp v42, v42, v42 row_bcast:31 row_mask:0xc bank_mask:0xf
	s_nop 1
	v_readlane_b32 vcc_lo, v42, 63
	s_nop 1
	v_mov_b32_e32 v18, vcc_lo
	v_mov_b32_e32 v42, 0
	s_and_saveexec_b64 s[76:77], s[40:41]
	s_cbranch_execz .LBB0_307
	s_waitcnt lgkmcnt(0)
	v_add_f32_e32 v18, v18, v42
	v_fmamk_f32 v18, v18, 0x3b800000, v51
	v_cmp_gt_f32_e32 vcc, s25, v18
	v_mul_f32_e32 v42, 0x4b800000, v18
	s_add_u32 s31, s52, s74
	v_cndmask_b32_e32 v18, v18, v42, vcc
	v_rsq_f32_e32 v18, v18
	s_addc_u32 s46, s53, s75
	s_lshl_b64 s[68:69], s[64:65], 10
	s_add_u32 s74, s31, s68
	v_mul_f32_e32 v42, 0x45800000, v18
	v_cndmask_b32_e32 v18, v18, v42, vcc
	v_pk_mul_f32 v[8:9], v[18:19], v[8:9] op_sel_hi:[0,1]
	v_pk_mul_f32 v[12:13], v[18:19], v[12:13] op_sel_hi:[0,1]
	v_pk_mul_f32 v[10:11], v[18:19], v[10:11] op_sel_hi:[0,1]
	s_addc_u32 s75, s46, s69
	s_lshl_b64 s[68:69], s[62:63], 9
	v_pk_mul_f32 v[10:11], v[10:11], v[144:145]
	v_pk_mul_f32 v[54:55], v[8:9], v[140:141]
	v_pk_mul_f32 v[8:9], v[18:19], v[14:15] op_sel_hi:[0,1]
	v_pk_mul_f32 v[52:53], v[12:13], v[138:139]
	v_pk_mul_f32 v[8:9], v[8:9], v[142:143]
	v_lshlrev_b32_e32 v12, 2, v20
	global_store_dwordx4 v12, v[52:55], s[74:75]
	global_store_dwordx4 v12, v[8:11], s[74:75] offset:16
	v_cvt_pk_bf16_f32 v12, v52, v53
	v_cvt_pk_bf16_f32 v13, v54, v55
	v_cvt_pk_bf16_f32 v14, v8, v9
	v_cvt_pk_bf16_f32 v15, v10, v11
	v_lshl_add_u64 v[8:9], v[28:29], 0, s[68:69]
	global_store_dwordx4 v[8:9], v[12:15], off
.LBB0_307:
	s_or_b64 exec, exec, s[76:77]
	v_mov_b32_e32 v8, 0
	s_and_saveexec_b64 s[74:75], s[42:43]
	s_cbranch_execz .LBB0_309
	s_add_u32 s31, s52, s66
	s_addc_u32 s33, s53, s67
	s_lshl_b64 s[64:65], s[64:65], 7
	s_add_u32 s64, s31, s64
	v_lshlrev_b32_e32 v18, 2, v16
	s_addc_u32 s65, s33, s65
	s_lshl_b64 s[66:67], s[62:63], 7
	v_lshl_add_u64 v[12:13], v[30:31], 0, s[66:67]
	v_pk_mul_f32 v[10:11], v[40:41], v[148:149] op_sel:[1,0] op_sel_hi:[0,0]
	v_pk_fma_f32 v[14:15], v[40:41], v[150:151], v[10:11] op_sel_hi:[1,0,1] neg_lo:[0,0,1] neg_hi:[0,0,1]
	v_pk_fma_f32 v[8:9], v[40:41], v[150:151], v[10:11] op_sel_hi:[1,0,1]
	global_store_dword v18, v14, s[64:65]
	global_store_dword v18, v9, s[64:65] offset:64
	global_store_dword v[12:13], v14, off
	global_store_dword v[12:13], v9, off offset:64
	v_mov_b32_e32 v15, v9
	v_pk_mul_f32 v[8:9], v[14:15], v[14:15]
	s_nop 0
	v_add_f32_e32 v8, v8, v9

; __device__ __forceinline__ unsigned pk2(float lo, float hi) { f32x2_t v = {lo, hi}; bf16x2_t b = __builtin_convertvector(v, bf16x2_t); return __builtin_bit_cast(unsigned, b); }
; __device__ __forceinline__ float bflo(unsigned w) { return __uint_as_float(w << 16); }
; __device__ __forceinline__ float bfhi(unsigned w) { return __uint_as_float(w & 0xffff0000u); }
; #define A (*args_opaque((CArgs*)__builtin_amdgcn_kernarg_segment_ptr()))
; __device__ __forceinline__ void p2_rows(ArgsRef A, int lane, int wave) {
;     ...
;         { const u32x4 w = qw[u]; float v[8]; v[0] = bflo(w.x); v[1] = bfhi(w.x); v[2] = bflo(w.y); v[3] = bfhi(w.y); v[4] = bflo(w.z); v[5] = bfhi(w.z); v[6] = bflo(w.w); v[7] = bfhi(w.w); float ss = 0.f;
; #pragma unroll
;           for (int k = 0; k < 8; ++k) ss += v[k] * v[k];
;           const float rs = rsqrtf(wave_sum(ss) * (1.f / 384.f) + EPSF);
;           if (lane < 48) { const f32x4 g0 = *(const f32x4*)(A.in[9] + lane * 8), g1 = *(const f32x4*)(A.in[9] + lane * 8 + 4);
;             u32x4 o; o.x = pk2(v[0] * rs * g0.x, v[1] * rs * g0.y); o.y = pk2(v[2] * rs * g0.z, v[3] * rs * g0.w); o.z = pk2(v[4] * rs * g1.x, v[5] * rs * g1.y); o.w = pk2(v[6] * rs * g1.z, v[7] * rs * g1.w);
;             *(u32x4*)(CQ + (size_t)r * 384 + lane * 8) = o; } }
;         { const u32x4 w = kw[u]; float v[8]; v[0] = bflo(w.x); v[1] = bfhi(w.x); v[2] = bflo(w.y); v[3] = bfhi(w.y); v[4] = bflo(w.z); v[5] = bfhi(w.z); v[6] = bflo(w.w); v[7] = bfhi(w.w); float ss = 0.f;
; #pragma unroll
;           for (int k = 0; k < 8; ++k) ss += v[k] * v[k];
;           const float rs = rsqrtf(wave_sum(ss) * (1.f / 256.f) + EPSF);
;           if (lane < 32) { const f32x4 g0 = *(const f32x4*)(A.in[11] + lane * 8), g1 = *(const f32x4*)(A.in[11] + lane * 8 + 4);
;             f32x4 c0, c1; c0.x = v[0] * rs * g0.x; c0.y = v[1] * rs * g0.y; c0.z = v[2] * rs * g0.z; c0.w = v[3] * rs * g0.w; c1.x = v[4] * rs * g1.x; c1.y = v[5] * rs * g1.y; c1.z = v[6] * rs * g1.z; c1.w = v[7] * rs * g1.w;
;             *(f32x4*)(okv + lane * 8) = c0; *(f32x4*)(okv + lane * 8 + 4) = c1;
;             u32x4 o; o.x = pk2(c0.x, c0.y); o.y = pk2(c0.z, c0.w); o.z = pk2(c1.x, c1.y); o.w = pk2(c1.z, c1.w);
;             *(u32x4*)(CKV + kvrow * 256 + lane * 8) = o; } }
.LBB0_317:
	v_lshlrev_b32_e32 v8, 16, v4
	s_waitcnt lgkmcnt(0)
	v_and_b32_e32 v9, 0xffff0000, v4
	v_lshlrev_b32_e32 v10, 16, v5
	v_and_b32_e32 v11, 0xffff0000, v5
	v_pk_mul_f32 v[12:13], v[8:9], v[8:9]
	v_pk_mul_f32 v[14:15], v[10:11], v[10:11]
	v_add_f32_e32 v12, v12, v13
	v_lshlrev_b32_e32 v4, 16, v6
	v_and_b32_e32 v5, 0xffff0000, v6
	v_add_f32_e32 v12, v14, v12
	v_pk_mul_f32 v[40:41], v[4:5], v[4:5]
	v_add_f32_e32 v12, v15, v12
	v_lshlrev_b32_e32 v6, 16, v7
	v_and_b32_e32 v7, 0xffff0000, v7
	v_add_f32_e32 v12, v40, v12
	v_pk_mul_f32 v[42:43], v[6:7], v[6:7]
	v_add_f32_e32 v12, v41, v12
	v_add_f32_e32 v12, v42, v12
	v_add_f32_e32 v12, v43, v12
	s_nop 1
	v_add_f32_dpp v13, v12, v12 quad_perm:[1,0,3,2] row_mask:0xf bank_mask:0xf
	s_nop 1
	v_add_f32_dpp v13, v13, v13 quad_perm:[2,3,0,1] row_mask:0xf bank_mask:0xf
	s_nop 1
	v_add_f32_dpp v13, v13, v13 row_half_mirror row_mask:0xf bank_mask:0xf
	s_nop 1
	v_add_f32_dpp v13, v13, v13 row_mirror row_mask:0xf bank_mask:0xf
	s_nop 1
	v_add_f32_dpp v13, v13, v13 row_bcast:15 row_mask:0xa bank_mask:0xf
	s_nop 1
	v_add_f32_dpp v13, v13, v13 row_bcast:31 row_mask:0xc bank_mask:0xf
	s_nop 1
	v_readlane_b32 vcc_lo, v13, 63
	s_nop 1
	v_mov_b32_e32 v12, vcc_lo
	v_mov_b32_e32 v13, 0
	s_and_saveexec_b64 s[66:67], s[38:39]
	s_cbranch_execz .LBB0_319
	s_waitcnt lgkmcnt(0)
	v_add_f32_e32 v12, v12, v13
	v_fmamk_f32 v12, v12, 0x3b2aaaab, v51
	v_mul_f32_e32 v13, 0x4b800000, v12
	v_cmp_gt_f32_e32 vcc, s25, v12
	s_nop 1
	v_cndmask_b32_e32 v12, v12, v13, vcc
	v_rsq_f32_e32 v12, v12
	s_nop 0
	v_mul_f32_e32 v13, 0x45800000, v12
	v_cndmask_b32_e32 v12, v12, v13, vcc
	v_pk_mul_f32 v[8:9], v[12:13], v[8:9] op_sel_hi:[0,1]
	v_pk_mul_f32 v[10:11], v[12:13], v[10:11] op_sel_hi:[0,1]
	v_pk_mul_f32 v[4:5], v[12:13], v[4:5] op_sel_hi:[0,1]
	v_pk_mul_f32 v[6:7], v[12:13], v[6:7] op_sel_hi:[0,1]
	v_pk_mul_f32 v[8:9], v[8:9], v[130:131]
	v_pk_mul_f32 v[10:11], v[10:11], v[132:133]
	v_pk_mul_f32 v[12:13], v[4:5], v[134:135]
	v_pk_mul_f32 v[14:15], v[6:7], v[136:137]
	v_cvt_pk_bf16_f32 v4, v8, v9
	v_cvt_pk_bf16_f32 v5, v10, v11
	v_cvt_pk_bf16_f32 v6, v12, v13
	v_cvt_pk_bf16_f32 v7, v14, v15
	v_mad_i64_i32 v[8:9], s[58:59], s58, v50, v[24:25]
	global_store_dwordx4 v[8:9], v[4:7], off
.LBB0_319:
	s_or_b64 exec, exec, s[66:67]
	s_nop 0
	v_lshlrev_b32_e32 v4, 16, v0
	v_and_b32_e32 v5, 0xffff0000, v0
	v_lshlrev_b32_e32 v0, 16, v1
	v_and_b32_e32 v1, 0xffff0000, v1
	v_pk_mul_f32 v[8:9], v[4:5], v[4:5]
	v_pk_mul_f32 v[10:11], v[0:1], v[0:1]
	v_add_f32_e32 v8, v8, v9
	v_lshlrev_b32_e32 v6, 16, v2
	v_and_b32_e32 v7, 0xffff0000, v2
	v_add_f32_e32 v8, v10, v8
	s_waitcnt lgkmcnt(0)
	v_pk_mul_f32 v[12:13], v[6:7], v[6:7]
	v_add_f32_e32 v8, v11, v8
	v_lshlrev_b32_e32 v2, 16, v3
	v_and_b32_e32 v3, 0xffff0000, v3
	v_add_f32_e32 v8, v12, v8
	v_pk_mul_f32 v[14:15], v[2:3], v[2:3]
	v_add_f32_e32 v8, v13, v8
	v_add_f32_e32 v8, v14, v8
	v_add_f32_e32 v8, v15, v8
	s_nop 1
	v_add_f32_dpp v9, v8, v8 quad_perm:[1,0,3,2] row_mask:0xf bank_mask:0xf
	s_nop 1
	v_add_f32_dpp v9, v9, v9 quad_perm:[2,3,0,1] row_mask:0xf bank_mask:0xf
	s_nop 1
	v_add_f32_dpp v9, v9, v9 row_half_mirror row_mask:0xf bank_mask:0xf
	s_nop 1
	v_add_f32_dpp v9, v9, v9 row_mirror row_mask:0xf bank_mask:0xf
	s_nop 1
	v_add_f32_dpp v9, v9, v9 row_bcast:15 row_mask:0xa bank_mask:0xf
	s_nop 1
	v_add_f32_dpp v9, v9, v9 row_bcast:31 row_mask:0xc bank_mask:0xf
	s_nop 1
	v_readlane_b32 vcc_lo, v9, 63
	s_nop 1
	v_mov_b32_e32 v8, vcc_lo
	v_mov_b32_e32 v9, 0
	s_and_saveexec_b64 s[58:59], s[40:41]
	s_cbranch_execz .LBB0_321
	s_waitcnt lgkmcnt(0)
	v_add_f32_e32 v8, v8, v9
	v_fmamk_f32 v8, v8, 0x3b800000, v51
	v_cmp_gt_f32_e32 vcc, s25, v8
	v_mul_f32_e32 v9, 0x4b800000, v8
	s_add_u32 s33, s52, s64
	v_cndmask_b32_e32 v8, v8, v9, vcc
	v_rsq_f32_e32 v8, v8
	s_addc_u32 s46, s53, s65
	s_lshl_b64 s[64:65], s[56:57], 10
	s_add_u32 s64, s33, s64
	v_mul_f32_e32 v9, 0x45800000, v8
	v_cndmask_b32_e32 v18, v8, v9, vcc
	v_pk_mul_f32 v[4:5], v[18:19], v[4:5] op_sel_hi:[0,1]
	v_pk_mul_f32 v[0:1], v[18:19], v[0:1] op_sel_hi:[0,1]
	s_addc_u32 s65, s46, s65
	v_pk_mul_f32 v[2:3], v[18:19], v[2:3] op_sel_hi:[0,1]
	v_pk_mul_f32 v[2:3], v[2:3], v[144:145]
	v_pk_mul_f32 v[12:13], v[4:5], v[138:139]
	v_pk_mul_f32 v[14:15], v[0:1], v[140:141]
	v_pk_mul_f32 v[0:1], v[18:19], v[6:7] op_sel_hi:[0,1]
	v_lshlrev_b32_e32 v4, 2, v20
	v_pk_mul_f32 v[0:1], v[0:1], v[142:143]
	global_store_dwordx4 v4, v[12:15], s[64:65]
	global_store_dwordx4 v4, v[0:3], s[64:65] offset:16
	s_lshl_b64 s[64:65], s[60:61], 9
	v_cvt_pk_bf16_f32 v4, v12, v13
	v_cvt_pk_bf16_f32 v5, v14, v15
	v_cvt_pk_bf16_f32 v6, v0, v1
	v_cvt_pk_bf16_f32 v7, v2, v3
	v_lshl_add_u64 v[0:1], v[28:29], 0, s[64:65]
	global_store_dwordx4 v[0:1], v[4:7], off
